# PEER stage B: norm gain slice loaded once per slice instead of per unit (removes hot-spot reloads of the same lines)
# speedup vs baseline: 1.2450x; 1.0171x over previous
.Lpb_slice:
	s_mov_b32 s17, 0
	s_lshl_b32 s1, s16, 9
	s_add_u32 s36, s6, s1
	s_addc_u32 s37, s7, 0
	global_load_dwordx4 v[128:131], v189, s[36:37]
	global_load_dwordx4 v[132:135], v189, s[36:37] offset:16
	global_load_dwordx4 v[136:139], v189, s[36:37] offset:32
	global_load_dwordx4 v[140:143], v189, s[36:37] offset:48
	s_lshr_b32 s0, s16, 1
	s_cmp_eq_u32 s0, s45
	s_cselect_b32 s43, 9, 8
.Lpb_unit:
	s_lshl_b32 s0, s17, 11
	s_add_i32 s0, s0, s27
	s_cmp_eq_u32 s17, 8
	s_cselect_b32 s0, s44, s0
	s_lshl_b32 s1, s16, 9
	s_lshl_b32 s24, s0, 12
	s_add_u32 s24, s24, s1
	s_add_u32 s20, s4, s24
	s_addc_u32 s21, s5, 0
	s_add_u32 s36, s6, s1
	s_addc_u32 s37, s7, 0
	s_lshl_b32 s25, s16, 21
	s_add_u32 s18, s8, s25
	s_addc_u32 s19, s9, 0
	s_lshl_b32 s25, s17, 9
	v_add_u32_e32 v205, s25, v190
	v_add_u32_e32 v210, s25, v209
	s_lshl_b32 s25, s17, 2
	v_add_u32_e32 v206, s25, v204
	ds_read_b128 v[64:67], v205
	ds_read_b128 v[68:71], v205 offset:16
	ds_read_b128 v[72:75], v205 offset:32
	ds_read_b128 v[76:79], v205 offset:48
	ds_read_b32 v208, v206
	global_load_dwordx4 v[80:83], v189, s[20:21]
	global_load_dwordx4 v[84:87], v189, s[20:21] offset:16
	global_load_dwordx4 v[88:91], v189, s[20:21] offset:32
	global_load_dwordx4 v[92:95], v189, s[20:21] offset:48
	s_waitcnt lgkmcnt(1)
	v_add_u32_e32 v64, v64, v188
	v_add_u32_e32 v65, v65, v188
	v_add_u32_e32 v66, v66, v188
	v_add_u32_e32 v67, v67, v188
	v_add_u32_e32 v68, v68, v188
	v_add_u32_e32 v69, v69, v188
	v_add_u32_e32 v70, v70, v188
	v_add_u32_e32 v71, v71, v188
	v_add_u32_e32 v72, v72, v188
	v_add_u32_e32 v73, v73, v188
	v_add_u32_e32 v74, v74, v188
	v_add_u32_e32 v75, v75, v188
	v_add_u32_e32 v76, v76, v188
	v_add_u32_e32 v77, v77, v188
	v_add_u32_e32 v78, v78, v188
	v_add_u32_e32 v79, v79, v188
	global_load_dwordx4 v[0:3], v64, s[18:19]
	global_load_dwordx4 v[4:7], v65, s[18:19]
	global_load_dwordx4 v[8:11], v66, s[18:19]
	global_load_dwordx4 v[12:15], v67, s[18:19]
	global_load_dwordx4 v[16:19], v68, s[18:19]
	global_load_dwordx4 v[20:23], v69, s[18:19]
	global_load_dwordx4 v[24:27], v70, s[18:19]
	global_load_dwordx4 v[28:31], v71, s[18:19]
	global_load_dwordx4 v[32:35], v72, s[18:19]
	global_load_dwordx4 v[36:39], v73, s[18:19]
	global_load_dwordx4 v[40:43], v74, s[18:19]
	global_load_dwordx4 v[44:47], v75, s[18:19]
	global_load_dwordx4 v[48:51], v76, s[18:19]
	global_load_dwordx4 v[52:55], v77, s[18:19]
	global_load_dwordx4 v[56:59], v78, s[18:19]
	global_load_dwordx4 v[60:63], v79, s[18:19]
	s_waitcnt vmcnt(16) lgkmcnt(0)
	v_pk_mul_f32 v[96:97], v[128:129], v[208:209] op_sel_hi:[1,0]
	v_pk_mul_f32 v[98:99], v[130:131], v[208:209] op_sel_hi:[1,0]
	v_pk_mul_f32 v[100:101], v[132:133], v[208:209] op_sel_hi:[1,0]
	v_pk_mul_f32 v[102:103], v[134:135], v[208:209] op_sel_hi:[1,0]
	v_pk_mul_f32 v[104:105], v[136:137], v[208:209] op_sel_hi:[1,0]
	v_pk_mul_f32 v[106:107], v[138:139], v[208:209] op_sel_hi:[1,0]
	v_pk_mul_f32 v[108:109], v[140:141], v[208:209] op_sel_hi:[1,0]
	v_pk_mul_f32 v[110:111], v[142:143], v[208:209] op_sel_hi:[1,0]
	v_pk_mul_f32 v[80:81], v[80:81], v[96:97]
	v_pk_mul_f32 v[82:83], v[82:83], v[98:99]
	v_pk_mul_f32 v[84:85], v[84:85], v[100:101]
	v_pk_mul_f32 v[86:87], v[86:87], v[102:103]
	v_pk_mul_f32 v[88:89], v[88:89], v[104:105]
	v_pk_mul_f32 v[90:91], v[90:91], v[106:107]
	v_pk_mul_f32 v[92:93], v[92:93], v[108:109]
	v_pk_mul_f32 v[94:95], v[94:95], v[110:111]
	s_waitcnt vmcnt(15)
	v_cvt_pk_f32_fp8_e32 v[168:169], v0
	v_cvt_pk_f32_fp8_sdwa v[170:171], v0 src0_sel:WORD_1
	v_cvt_pk_f32_fp8_e32 v[172:173], v1
	v_cvt_pk_f32_fp8_sdwa v[174:175], v1 src0_sel:WORD_1
	v_cvt_pk_f32_fp8_e32 v[176:177], v2
	v_cvt_pk_f32_fp8_sdwa v[178:179], v2 src0_sel:WORD_1
	v_cvt_pk_f32_fp8_e32 v[180:181], v3
	v_cvt_pk_f32_fp8_sdwa v[182:183], v3 src0_sel:WORD_1
	v_pk_mul_f32 v[184:185], v[168:169], v[80:81]
	v_pk_mul_f32 v[186:187], v[170:171], v[82:83]
	v_pk_fma_f32 v[184:185], v[172:173], v[84:85], v[184:185]
	v_pk_fma_f32 v[186:187], v[174:175], v[86:87], v[186:187]
	v_pk_fma_f32 v[184:185], v[176:177], v[88:89], v[184:185]
	v_pk_fma_f32 v[186:187], v[178:179], v[90:91], v[186:187]
	v_pk_fma_f32 v[184:185], v[180:181], v[92:93], v[184:185]
	v_pk_fma_f32 v[186:187], v[182:183], v[94:95], v[186:187]
	v_pk_add_f32 v[184:185], v[184:185], v[186:187]
	v_add_f32_e32 v112, v184, v185
	s_waitcnt vmcnt(14)
	v_cvt_pk_f32_fp8_e32 v[168:169], v4
	v_cvt_pk_f32_fp8_sdwa v[170:171], v4 src0_sel:WORD_1
	v_cvt_pk_f32_fp8_e32 v[172:173], v5
	v_cvt_pk_f32_fp8_sdwa v[174:175], v5 src0_sel:WORD_1
	v_cvt_pk_f32_fp8_e32 v[176:177], v6
	v_cvt_pk_f32_fp8_sdwa v[178:179], v6 src0_sel:WORD_1
	v_cvt_pk_f32_fp8_e32 v[180:181], v7
	v_cvt_pk_f32_fp8_sdwa v[182:183], v7 src0_sel:WORD_1
	v_pk_mul_f32 v[184:185], v[168:169], v[80:81]
	v_pk_mul_f32 v[186:187], v[170:171], v[82:83]
	v_pk_fma_f32 v[184:185], v[172:173], v[84:85], v[184:185]
	v_pk_fma_f32 v[186:187], v[174:175], v[86:87], v[186:187]
	v_pk_fma_f32 v[184:185], v[176:177], v[88:89], v[184:185]
	v_pk_fma_f32 v[186:187], v[178:179], v[90:91], v[186:187]
	v_pk_fma_f32 v[184:185], v[180:181], v[92:93], v[184:185]
	v_pk_fma_f32 v[186:187], v[182:183], v[94:95], v[186:187]
	v_pk_add_f32 v[184:185], v[184:185], v[186:187]
	v_add_f32_e32 v113, v184, v185
	s_waitcnt vmcnt(13)
	v_cvt_pk_f32_fp8_e32 v[168:169], v8
	v_cvt_pk_f32_fp8_sdwa v[170:171], v8 src0_sel:WORD_1
	v_cvt_pk_f32_fp8_e32 v[172:173], v9
	v_cvt_pk_f32_fp8_sdwa v[174:175], v9 src0_sel:WORD_1
	v_cvt_pk_f32_fp8_e32 v[176:177], v10
	v_cvt_pk_f32_fp8_sdwa v[178:179], v10 src0_sel:WORD_1
	v_cvt_pk_f32_fp8_e32 v[180:181], v11
	v_cvt_pk_f32_fp8_sdwa v[182:183], v11 src0_sel:WORD_1
	v_pk_mul_f32 v[184:185], v[168:169], v[80:81]
	v_pk_mul_f32 v[186:187], v[170:171], v[82:83]
	v_pk_fma_f32 v[184:185], v[172:173], v[84:85], v[184:185]
	v_pk_fma_f32 v[186:187], v[174:175], v[86:87], v[186:187]
	v_pk_fma_f32 v[184:185], v[176:177], v[88:89], v[184:185]
	v_pk_fma_f32 v[186:187], v[178:179], v[90:91], v[186:187]
	v_pk_fma_f32 v[184:185], v[180:181], v[92:93], v[184:185]
	v_pk_fma_f32 v[186:187], v[182:183], v[94:95], v[186:187]
	v_pk_add_f32 v[184:185], v[184:185], v[186:187]
	v_add_f32_e32 v114, v184, v185
	s_waitcnt vmcnt(12)
	v_cvt_pk_f32_fp8_e32 v[168:169], v12
	v_cvt_pk_f32_fp8_sdwa v[170:171], v12 src0_sel:WORD_1
	v_cvt_pk_f32_fp8_e32 v[172:173], v13
	v_cvt_pk_f32_fp8_sdwa v[174:175], v13 src0_sel:WORD_1
	v_cvt_pk_f32_fp8_e32 v[176:177], v14
	v_cvt_pk_f32_fp8_sdwa v[178:179], v14 src0_sel:WORD_1
	v_cvt_pk_f32_fp8_e32 v[180:181], v15
	v_cvt_pk_f32_fp8_sdwa v[182:183], v15 src0_sel:WORD_1
	v_pk_mul_f32 v[184:185], v[168:169], v[80:81]
	v_pk_mul_f32 v[186:187], v[170:171], v[82:83]
	v_pk_fma_f32 v[184:185], v[172:173], v[84:85], v[184:185]
	v_pk_fma_f32 v[186:187], v[174:175], v[86:87], v[186:187]
	v_pk_fma_f32 v[184:185], v[176:177], v[88:89], v[184:185]
	v_pk_fma_f32 v[186:187], v[178:179], v[90:91], v[186:187]
	v_pk_fma_f32 v[184:185], v[180:181], v[92:93], v[184:185]
	v_pk_fma_f32 v[186:187], v[182:183], v[94:95], v[186:187]
	v_pk_add_f32 v[184:185], v[184:185], v[186:187]
	v_add_f32_e32 v115, v184, v185
	s_waitcnt vmcnt(11)
	v_cvt_pk_f32_fp8_e32 v[168:169], v16
	v_cvt_pk_f32_fp8_sdwa v[170:171], v16 src0_sel:WORD_1
	v_cvt_pk_f32_fp8_e32 v[172:173], v17
	v_cvt_pk_f32_fp8_sdwa v[174:175], v17 src0_sel:WORD_1
	v_cvt_pk_f32_fp8_e32 v[176:177], v18
	v_cvt_pk_f32_fp8_sdwa v[178:179], v18 src0_sel:WORD_1
	v_cvt_pk_f32_fp8_e32 v[180:181], v19
	v_cvt_pk_f32_fp8_sdwa v[182:183], v19 src0_sel:WORD_1
	v_pk_mul_f32 v[184:185], v[168:169], v[80:81]
	v_pk_mul_f32 v[186:187], v[170:171], v[82:83]
	v_pk_fma_f32 v[184:185], v[172:173], v[84:85], v[184:185]
	v_pk_fma_f32 v[186:187], v[174:175], v[86:87], v[186:187]
	v_pk_fma_f32 v[184:185], v[176:177], v[88:89], v[184:185]
	v_pk_fma_f32 v[186:187], v[178:179], v[90:91], v[186:187]
	v_pk_fma_f32 v[184:185], v[180:181], v[92:93], v[184:185]
	v_pk_fma_f32 v[186:187], v[182:183], v[94:95], v[186:187]
	v_pk_add_f32 v[184:185], v[184:185], v[186:187]
	v_add_f32_e32 v116, v184, v185
	s_waitcnt vmcnt(10)
	v_cvt_pk_f32_fp8_e32 v[168:169], v20
	v_cvt_pk_f32_fp8_sdwa v[170:171], v20 src0_sel:WORD_1
	v_cvt_pk_f32_fp8_e32 v[172:173], v21
	v_cvt_pk_f32_fp8_sdwa v[174:175], v21 src0_sel:WORD_1
	v_cvt_pk_f32_fp8_e32 v[176:177], v22
	v_cvt_pk_f32_fp8_sdwa v[178:179], v22 src0_sel:WORD_1
	v_cvt_pk_f32_fp8_e32 v[180:181], v23
	v_cvt_pk_f32_fp8_sdwa v[182:183], v23 src0_sel:WORD_1
	v_pk_mul_f32 v[184:185], v[168:169], v[80:81]
	v_pk_mul_f32 v[186:187], v[170:171], v[82:83]
	v_pk_fma_f32 v[184:185], v[172:173], v[84:85], v[184:185]
	v_pk_fma_f32 v[186:187], v[174:175], v[86:87], v[186:187]
	v_pk_fma_f32 v[184:185], v[176:177], v[88:89], v[184:185]
	v_pk_fma_f32 v[186:187], v[178:179], v[90:91], v[186:187]
	v_pk_fma_f32 v[184:185], v[180:181], v[92:93], v[184:185]
	v_pk_fma_f32 v[186:187], v[182:183], v[94:95], v[186:187]
	v_pk_add_f32 v[184:185], v[184:185], v[186:187]
	v_add_f32_e32 v117, v184, v185
	s_waitcnt vmcnt(9)
	v_cvt_pk_f32_fp8_e32 v[168:169], v24
	v_cvt_pk_f32_fp8_sdwa v[170:171], v24 src0_sel:WORD_1
	v_cvt_pk_f32_fp8_e32 v[172:173], v25
	v_cvt_pk_f32_fp8_sdwa v[174:175], v25 src0_sel:WORD_1
	v_cvt_pk_f32_fp8_e32 v[176:177], v26
	v_cvt_pk_f32_fp8_sdwa v[178:179], v26 src0_sel:WORD_1
	v_cvt_pk_f32_fp8_e32 v[180:181], v27
	v_cvt_pk_f32_fp8_sdwa v[182:183], v27 src0_sel:WORD_1
	v_pk_mul_f32 v[184:185], v[168:169], v[80:81]
	v_pk_mul_f32 v[186:187], v[170:171], v[82:83]
	v_pk_fma_f32 v[184:185], v[172:173], v[84:85], v[184:185]
	v_pk_fma_f32 v[186:187], v[174:175], v[86:87], v[186:187]
	v_pk_fma_f32 v[184:185], v[176:177], v[88:89], v[184:185]
	v_pk_fma_f32 v[186:187], v[178:179], v[90:91], v[186:187]
	v_pk_fma_f32 v[184:185], v[180:181], v[92:93], v[184:185]
	v_pk_fma_f32 v[186:187], v[182:183], v[94:95], v[186:187]
	v_pk_add_f32 v[184:185], v[184:185], v[186:187]
	v_add_f32_e32 v118, v184, v185
	s_waitcnt vmcnt(8)
	v_cvt_pk_f32_fp8_e32 v[168:169], v28
	v_cvt_pk_f32_fp8_sdwa v[170:171], v28 src0_sel:WORD_1
	v_cvt_pk_f32_fp8_e32 v[172:173], v29
	v_cvt_pk_f32_fp8_sdwa v[174:175], v29 src0_sel:WORD_1
	v_cvt_pk_f32_fp8_e32 v[176:177], v30
	v_cvt_pk_f32_fp8_sdwa v[178:179], v30 src0_sel:WORD_1
	v_cvt_pk_f32_fp8_e32 v[180:181], v31
	v_cvt_pk_f32_fp8_sdwa v[182:183], v31 src0_sel:WORD_1
	v_pk_mul_f32 v[184:185], v[168:169], v[80:81]
	v_pk_mul_f32 v[186:187], v[170:171], v[82:83]
	v_pk_fma_f32 v[184:185], v[172:173], v[84:85], v[184:185]
	v_pk_fma_f32 v[186:187], v[174:175], v[86:87], v[186:187]
	v_pk_fma_f32 v[184:185], v[176:177], v[88:89], v[184:185]
	v_pk_fma_f32 v[186:187], v[178:179], v[90:91], v[186:187]
	v_pk_fma_f32 v[184:185], v[180:181], v[92:93], v[184:185]
	v_pk_fma_f32 v[186:187], v[182:183], v[94:95], v[186:187]
	v_pk_add_f32 v[184:185], v[184:185], v[186:187]
	v_add_f32_e32 v119, v184, v185
	s_waitcnt vmcnt(7)
	v_cvt_pk_f32_fp8_e32 v[168:169], v32
	v_cvt_pk_f32_fp8_sdwa v[170:171], v32 src0_sel:WORD_1
	v_cvt_pk_f32_fp8_e32 v[172:173], v33
	v_cvt_pk_f32_fp8_sdwa v[174:175], v33 src0_sel:WORD_1
	v_cvt_pk_f32_fp8_e32 v[176:177], v34
	v_cvt_pk_f32_fp8_sdwa v[178:179], v34 src0_sel:WORD_1
	v_cvt_pk_f32_fp8_e32 v[180:181], v35
	v_cvt_pk_f32_fp8_sdwa v[182:183], v35 src0_sel:WORD_1
	v_pk_mul_f32 v[184:185], v[168:169], v[80:81]
	v_pk_mul_f32 v[186:187], v[170:171], v[82:83]
	v_pk_fma_f32 v[184:185], v[172:173], v[84:85], v[184:185]
	v_pk_fma_f32 v[186:187], v[174:175], v[86:87], v[186:187]
	v_pk_fma_f32 v[184:185], v[176:177], v[88:89], v[184:185]
	v_pk_fma_f32 v[186:187], v[178:179], v[90:91], v[186:187]
	v_pk_fma_f32 v[184:185], v[180:181], v[92:93], v[184:185]
	v_pk_fma_f32 v[186:187], v[182:183], v[94:95], v[186:187]
	v_pk_add_f32 v[184:185], v[184:185], v[186:187]
	v_add_f32_e32 v120, v184, v185
	s_waitcnt vmcnt(6)
	v_cvt_pk_f32_fp8_e32 v[168:169], v36
	v_cvt_pk_f32_fp8_sdwa v[170:171], v36 src0_sel:WORD_1
	v_cvt_pk_f32_fp8_e32 v[172:173], v37
	v_cvt_pk_f32_fp8_sdwa v[174:175], v37 src0_sel:WORD_1
	v_cvt_pk_f32_fp8_e32 v[176:177], v38
	v_cvt_pk_f32_fp8_sdwa v[178:179], v38 src0_sel:WORD_1
	v_cvt_pk_f32_fp8_e32 v[180:181], v39
	v_cvt_pk_f32_fp8_sdwa v[182:183], v39 src0_sel:WORD_1
	v_pk_mul_f32 v[184:185], v[168:169], v[80:81]
	v_pk_mul_f32 v[186:187], v[170:171], v[82:83]
	v_pk_fma_f32 v[184:185], v[172:173], v[84:85], v[184:185]
	v_pk_fma_f32 v[186:187], v[174:175], v[86:87], v[186:187]
	v_pk_fma_f32 v[184:185], v[176:177], v[88:89], v[184:185]
	v_pk_fma_f32 v[186:187], v[178:179], v[90:91], v[186:187]
	v_pk_fma_f32 v[184:185], v[180:181], v[92:93], v[184:185]
	v_pk_fma_f32 v[186:187], v[182:183], v[94:95], v[186:187]
	v_pk_add_f32 v[184:185], v[184:185], v[186:187]
	v_add_f32_e32 v121, v184, v185
	s_waitcnt vmcnt(5)
	v_cvt_pk_f32_fp8_e32 v[168:169], v40
	v_cvt_pk_f32_fp8_sdwa v[170:171], v40 src0_sel:WORD_1
	v_cvt_pk_f32_fp8_e32 v[172:173], v41
	v_cvt_pk_f32_fp8_sdwa v[174:175], v41 src0_sel:WORD_1
	v_cvt_pk_f32_fp8_e32 v[176:177], v42
	v_cvt_pk_f32_fp8_sdwa v[178:179], v42 src0_sel:WORD_1
	v_cvt_pk_f32_fp8_e32 v[180:181], v43
	v_cvt_pk_f32_fp8_sdwa v[182:183], v43 src0_sel:WORD_1
	v_pk_mul_f32 v[184:185], v[168:169], v[80:81]
	v_pk_mul_f32 v[186:187], v[170:171], v[82:83]
	v_pk_fma_f32 v[184:185], v[172:173], v[84:85], v[184:185]
	v_pk_fma_f32 v[186:187], v[174:175], v[86:87], v[186:187]
	v_pk_fma_f32 v[184:185], v[176:177], v[88:89], v[184:185]
	v_pk_fma_f32 v[186:187], v[178:179], v[90:91], v[186:187]
	v_pk_fma_f32 v[184:185], v[180:181], v[92:93], v[184:185]
	v_pk_fma_f32 v[186:187], v[182:183], v[94:95], v[186:187]
	v_pk_add_f32 v[184:185], v[184:185], v[186:187]
	v_add_f32_e32 v122, v184, v185
	s_waitcnt vmcnt(4)
	v_cvt_pk_f32_fp8_e32 v[168:169], v44
	v_cvt_pk_f32_fp8_sdwa v[170:171], v44 src0_sel:WORD_1
	v_cvt_pk_f32_fp8_e32 v[172:173], v45
	v_cvt_pk_f32_fp8_sdwa v[174:175], v45 src0_sel:WORD_1
	v_cvt_pk_f32_fp8_e32 v[176:177], v46
	v_cvt_pk_f32_fp8_sdwa v[178:179], v46 src0_sel:WORD_1
	v_cvt_pk_f32_fp8_e32 v[180:181], v47
	v_cvt_pk_f32_fp8_sdwa v[182:183], v47 src0_sel:WORD_1
	v_pk_mul_f32 v[184:185], v[168:169], v[80:81]
	v_pk_mul_f32 v[186:187], v[170:171], v[82:83]
	v_pk_fma_f32 v[184:185], v[172:173], v[84:85], v[184:185]
	v_pk_fma_f32 v[186:187], v[174:175], v[86:87], v[186:187]
	v_pk_fma_f32 v[184:185], v[176:177], v[88:89], v[184:185]
	v_pk_fma_f32 v[186:187], v[178:179], v[90:91], v[186:187]
	v_pk_fma_f32 v[184:185], v[180:181], v[92:93], v[184:185]
	v_pk_fma_f32 v[186:187], v[182:183], v[94:95], v[186:187]
	v_pk_add_f32 v[184:185], v[184:185], v[186:187]
	v_add_f32_e32 v123, v184, v185
	s_waitcnt vmcnt(3)
	v_cvt_pk_f32_fp8_e32 v[168:169], v48
	v_cvt_pk_f32_fp8_sdwa v[170:171], v48 src0_sel:WORD_1
	v_cvt_pk_f32_fp8_e32 v[172:173], v49
	v_cvt_pk_f32_fp8_sdwa v[174:175], v49 src0_sel:WORD_1
	v_cvt_pk_f32_fp8_e32 v[176:177], v50
	v_cvt_pk_f32_fp8_sdwa v[178:179], v50 src0_sel:WORD_1
	v_cvt_pk_f32_fp8_e32 v[180:181], v51
	v_cvt_pk_f32_fp8_sdwa v[182:183], v51 src0_sel:WORD_1
	v_pk_mul_f32 v[184:185], v[168:169], v[80:81]
	v_pk_mul_f32 v[186:187], v[170:171], v[82:83]
	v_pk_fma_f32 v[184:185], v[172:173], v[84:85], v[184:185]
	v_pk_fma_f32 v[186:187], v[174:175], v[86:87], v[186:187]
	v_pk_fma_f32 v[184:185], v[176:177], v[88:89], v[184:185]
	v_pk_fma_f32 v[186:187], v[178:179], v[90:91], v[186:187]
	v_pk_fma_f32 v[184:185], v[180:181], v[92:93], v[184:185]
	v_pk_fma_f32 v[186:187], v[182:183], v[94:95], v[186:187]
	v_pk_add_f32 v[184:185], v[184:185], v[186:187]
	v_add_f32_e32 v124, v184, v185
	s_waitcnt vmcnt(2)
	v_cvt_pk_f32_fp8_e32 v[168:169], v52
	v_cvt_pk_f32_fp8_sdwa v[170:171], v52 src0_sel:WORD_1
	v_cvt_pk_f32_fp8_e32 v[172:173], v53
	v_cvt_pk_f32_fp8_sdwa v[174:175], v53 src0_sel:WORD_1
	v_cvt_pk_f32_fp8_e32 v[176:177], v54
	v_cvt_pk_f32_fp8_sdwa v[178:179], v54 src0_sel:WORD_1
	v_cvt_pk_f32_fp8_e32 v[180:181], v55
	v_cvt_pk_f32_fp8_sdwa v[182:183], v55 src0_sel:WORD_1
	v_pk_mul_f32 v[184:185], v[168:169], v[80:81]
	v_pk_mul_f32 v[186:187], v[170:171], v[82:83]
	v_pk_fma_f32 v[184:185], v[172:173], v[84:85], v[184:185]
	v_pk_fma_f32 v[186:187], v[174:175], v[86:87], v[186:187]
	v_pk_fma_f32 v[184:185], v[176:177], v[88:89], v[184:185]
	v_pk_fma_f32 v[186:187], v[178:179], v[90:91], v[186:187]
	v_pk_fma_f32 v[184:185], v[180:181], v[92:93], v[184:185]
	v_pk_fma_f32 v[186:187], v[182:183], v[94:95], v[186:187]
	v_pk_add_f32 v[184:185], v[184:185], v[186:187]
	v_add_f32_e32 v125, v184, v185
	s_waitcnt vmcnt(1)
	v_cvt_pk_f32_fp8_e32 v[168:169], v56
	v_cvt_pk_f32_fp8_sdwa v[170:171], v56 src0_sel:WORD_1
	v_cvt_pk_f32_fp8_e32 v[172:173], v57
	v_cvt_pk_f32_fp8_sdwa v[174:175], v57 src0_sel:WORD_1
	v_cvt_pk_f32_fp8_e32 v[176:177], v58
	v_cvt_pk_f32_fp8_sdwa v[178:179], v58 src0_sel:WORD_1
	v_cvt_pk_f32_fp8_e32 v[180:181], v59
	v_cvt_pk_f32_fp8_sdwa v[182:183], v59 src0_sel:WORD_1
	v_pk_mul_f32 v[184:185], v[168:169], v[80:81]
	v_pk_mul_f32 v[186:187], v[170:171], v[82:83]
	v_pk_fma_f32 v[184:185], v[172:173], v[84:85], v[184:185]
	v_pk_fma_f32 v[186:187], v[174:175], v[86:87], v[186:187]
	v_pk_fma_f32 v[184:185], v[176:177], v[88:89], v[184:185]
	v_pk_fma_f32 v[186:187], v[178:179], v[90:91], v[186:187]
	v_pk_fma_f32 v[184:185], v[180:181], v[92:93], v[184:185]
	v_pk_fma_f32 v[186:187], v[182:183], v[94:95], v[186:187]
	v_pk_add_f32 v[184:185], v[184:185], v[186:187]
	v_add_f32_e32 v126, v184, v185
	s_waitcnt vmcnt(0)
	v_cvt_pk_f32_fp8_e32 v[168:169], v60
	v_cvt_pk_f32_fp8_sdwa v[170:171], v60 src0_sel:WORD_1
	v_cvt_pk_f32_fp8_e32 v[172:173], v61
	v_cvt_pk_f32_fp8_sdwa v[174:175], v61 src0_sel:WORD_1
	v_cvt_pk_f32_fp8_e32 v[176:177], v62
	v_cvt_pk_f32_fp8_sdwa v[178:179], v62 src0_sel:WORD_1
	v_cvt_pk_f32_fp8_e32 v[180:181], v63
	v_cvt_pk_f32_fp8_sdwa v[182:183], v63 src0_sel:WORD_1
	v_pk_mul_f32 v[184:185], v[168:169], v[80:81]
	v_pk_mul_f32 v[186:187], v[170:171], v[82:83]
	v_pk_fma_f32 v[184:185], v[172:173], v[84:85], v[184:185]
	v_pk_fma_f32 v[186:187], v[174:175], v[86:87], v[186:187]
	v_pk_fma_f32 v[184:185], v[176:177], v[88:89], v[184:185]
	v_pk_fma_f32 v[186:187], v[178:179], v[90:91], v[186:187]
	v_pk_fma_f32 v[184:185], v[180:181], v[92:93], v[184:185]
	v_pk_fma_f32 v[186:187], v[182:183], v[94:95], v[186:187]
	v_pk_add_f32 v[184:185], v[184:185], v[186:187]
	v_add_f32_e32 v127, v184, v185
	s_nop 1
	v_add_f32_dpp v160, v112, v112 row_half_mirror row_mask:0xf bank_mask:0x5
	v_add_f32_dpp v160, v113, v113 row_half_mirror row_mask:0xf bank_mask:0xa
	v_add_f32_dpp v161, v114, v114 row_half_mirror row_mask:0xf bank_mask:0x5
	v_add_f32_dpp v161, v115, v115 row_half_mirror row_mask:0xf bank_mask:0xa
	v_add_f32_dpp v162, v116, v116 row_half_mirror row_mask:0xf bank_mask:0x5
	v_add_f32_dpp v162, v117, v117 row_half_mirror row_mask:0xf bank_mask:0xa
	v_add_f32_dpp v163, v118, v118 row_half_mirror row_mask:0xf bank_mask:0x5
	v_add_f32_dpp v163, v119, v119 row_half_mirror row_mask:0xf bank_mask:0xa
	v_add_f32_dpp v164, v120, v120 row_half_mirror row_mask:0xf bank_mask:0x5
	v_add_f32_dpp v164, v121, v121 row_half_mirror row_mask:0xf bank_mask:0xa
	v_add_f32_dpp v165, v122, v122 row_half_mirror row_mask:0xf bank_mask:0x5
	v_add_f32_dpp v165, v123, v123 row_half_mirror row_mask:0xf bank_mask:0xa
	v_add_f32_dpp v166, v124, v124 row_half_mirror row_mask:0xf bank_mask:0x5
	v_add_f32_dpp v166, v125, v125 row_half_mirror row_mask:0xf bank_mask:0xa
	v_add_f32_dpp v167, v126, v126 row_half_mirror row_mask:0xf bank_mask:0x5
	v_add_f32_dpp v167, v127, v127 row_half_mirror row_mask:0xf bank_mask:0xa
	ds_read_b128 v[168:171], v210
	ds_read_b128 v[172:175], v210 offset:16
	s_nop 1
	v_add_f32_dpp v160, v160, v160 quad_perm:[1,0,3,2] row_mask:0xf bank_mask:0xf
	v_add_f32_dpp v161, v161, v161 quad_perm:[1,0,3,2] row_mask:0xf bank_mask:0xf
	v_add_f32_dpp v162, v162, v162 quad_perm:[1,0,3,2] row_mask:0xf bank_mask:0xf
	v_add_f32_dpp v163, v163, v163 quad_perm:[1,0,3,2] row_mask:0xf bank_mask:0xf
	v_add_f32_dpp v164, v164, v164 quad_perm:[1,0,3,2] row_mask:0xf bank_mask:0xf
	v_add_f32_dpp v165, v165, v165 quad_perm:[1,0,3,2] row_mask:0xf bank_mask:0xf
	v_add_f32_dpp v166, v166, v166 quad_perm:[1,0,3,2] row_mask:0xf bank_mask:0xf
	v_add_f32_dpp v167, v167, v167 quad_perm:[1,0,3,2] row_mask:0xf bank_mask:0xf
	s_nop 1
	v_add_f32_dpp v160, v160, v160 quad_perm:[2,3,0,1] row_mask:0xf bank_mask:0xf
	v_add_f32_dpp v161, v161, v161 quad_perm:[2,3,0,1] row_mask:0xf bank_mask:0xf
	v_add_f32_dpp v162, v162, v162 quad_perm:[2,3,0,1] row_mask:0xf bank_mask:0xf
	v_add_f32_dpp v163, v163, v163 quad_perm:[2,3,0,1] row_mask:0xf bank_mask:0xf
	v_add_f32_dpp v164, v164, v164 quad_perm:[2,3,0,1] row_mask:0xf bank_mask:0xf
	v_add_f32_dpp v165, v165, v165 quad_perm:[2,3,0,1] row_mask:0xf bank_mask:0xf
	v_add_f32_dpp v166, v166, v166 quad_perm:[2,3,0,1] row_mask:0xf bank_mask:0xf
	v_add_f32_dpp v167, v167, v167 quad_perm:[2,3,0,1] row_mask:0xf bank_mask:0xf
	s_waitcnt lgkmcnt(0)
	v_add_f32_e32 v168, v168, v160
	v_add_f32_e32 v169, v169, v161
	v_add_f32_e32 v170, v170, v162
	v_add_f32_e32 v171, v171, v163
	v_add_f32_e32 v172, v172, v164
	v_add_f32_e32 v173, v173, v165
	v_add_f32_e32 v174, v174, v166
	v_add_f32_e32 v175, v175, v167
	ds_write_b128 v210, v[168:171]
	ds_write_b128 v210, v[172:175] offset:16
	s_add_i32 s17, s17, 1
	s_cmp_lt_i32 s17, s43
	s_cbranch_scc1 .Lpb_unit
	s_add_i32 s16, s16, 1
	s_cmp_lt_i32 s16, 8
	s_cbranch_scc1 .Lpb_slice
	v_and_b32_e32 v160, 63, v218
	v_and_b32_e32 v161, 0x30, v160
	v_and_b32_e32 v162, 1, v160
	v_bfe_u32 v163, v160, 1, 3
	v_lshl_add_u32 v161, v162, 3, v161
	v_add_u32_e32 v161, v161, v163
	v_lshlrev_b32_e32 v161, 2, v161
	v_lshlrev_b32_e32 v160, 2, v160
	v_sub_u32_e32 v162, v202, v160
	v_add_u32_e32 v161, v161, v162
	v_add_u32_e32 v161, 0x2400, v161
	s_mov_b32 s17, 0
